# v27 with the permlane32 exchange done on the two P fragments instead of the four V fragments per key block (4 fewer VALU ops per block)
# baseline (speedup 1.0000x reference)
.LBB0_248:
	v_add_u32_e32 v32, s33, v96
	v_lshl_or_b32 v64, v32, 6, v75
	v_sub_u32_e32 v33, v32, v77
	v_cmp_ge_u32_e32 vcc, v32, v98
	v_cmp_lt_u32_e64 s[68:69], v32, v100
	v_add_u32_e32 v32, v99, v64
	v_max_i32_e32 v33, -7, v33
	v_mad_i64_i32 v[36:37], s[2:3], v32, s89, v[86:87]
	v_add_u32_e32 v38, 7, v33
	global_load_dwordx4 v[32:35], v[36:37], off offset:1024
	global_load_dwordx4 v[118:121], v[36:37], off offset:1056
	global_load_dwordx4 v[122:125], v[36:37], off offset:1088
	global_load_dwordx4 v[126:129], v[36:37], off offset:1120
	s_and_b64 s[84:85], vcc, s[68:69]
	v_min_u32_e32 v36, 14, v38
	s_movk_i32 vcc_lo, 0x7c
	v_mad_u32_u24 v130, v36, vcc_lo, v91
	v_lshl_add_u32 v160, v161, 2, v130
	ds_read_b32 v131, v160
	ds_read_b32 v132, v160 offset:4
	v_readlane_b32 s2, v254, 61
	v_readlane_b32 s3, v254, 62
	s_and_b64 s[2:3], s[84:85], s[2:3]
	s_and_b64 s[96:97], s[84:85], s[6:7]
	s_and_b64 s[94:95], s[84:85], s[10:11]
	s_and_b64 s[92:93], s[84:85], s[14:15]
	s_and_b64 s[96:97], s[96:97], s[8:9]
	s_and_b64 s[2:3], s[2:3], s[4:5]
	s_and_b64 s[90:91], s[84:85], s[18:19]
	s_and_b64 s[88:89], s[84:85], s[22:23]
	s_and_b64 s[94:95], s[94:95], s[12:13]
	s_and_b64 s[92:93], s[92:93], s[16:17]
	s_and_b64 s[86:87], s[84:85], s[26:27]
	s_and_b64 s[68:69], s[84:85], s[30:31]
	s_and_b64 s[90:91], s[90:91], s[20:21]
	s_and_b64 s[88:89], s[88:89], s[24:25]
	s_and_b64 s[70:71], s[84:85], s[36:37]
	s_and_b64 s[72:73], s[84:85], s[40:41]
	s_and_b64 s[86:87], s[86:87], s[28:29]
	s_and_b64 s[68:69], s[68:69], s[34:35]
	s_and_b64 s[74:75], s[84:85], s[44:45]
	s_and_b64 s[76:77], s[84:85], s[48:49]
	s_and_b64 s[70:71], s[70:71], s[38:39]
	s_and_b64 s[72:73], s[72:73], s[42:43]
	s_and_b64 s[78:79], s[84:85], s[52:53]
	s_and_b64 s[80:81], s[84:85], s[56:57]
	s_and_b64 s[74:75], s[74:75], s[46:47]
	s_and_b64 s[76:77], s[76:77], s[50:51]
	s_and_b64 s[82:83], s[84:85], s[60:61]
	s_and_b64 s[84:85], s[84:85], s[64:65]
	s_and_b64 s[78:79], s[78:79], s[54:55]
	s_and_b64 s[80:81], s[80:81], s[58:59]
	s_and_b64 s[82:83], s[82:83], s[62:63]
	s_and_b64 s[84:85], s[84:85], s[66:67]
	s_add_i32 s33, s33, 1
	v_cmp_ge_i32_e32 vcc, s33, v97
	s_or_b64 s[0:1], vcc, s[0:1]
	s_waitcnt vmcnt(3)
	v_mfma_f32_32x32x16_bf16 v[32:47], v[32:35], v[48:51], 0
	s_waitcnt vmcnt(2)
	v_mfma_f32_32x32x16_bf16 v[32:47], v[118:121], v[52:55], v[32:47]
	ds_read_b32 v118, v160 offset:8
	ds_read_b32 v119, v160 offset:12
	ds_read_b32 v120, v160 offset:32
	ds_read_b32 v121, v160 offset:36
	ds_read_b32 v133, v160 offset:40
	ds_read_b32 v134, v160 offset:44
	ds_read_b32 v135, v160 offset:64
	s_waitcnt vmcnt(1)
	v_mfma_f32_32x32x16_bf16 v[32:47], v[122:125], v[56:59], v[32:47]
	ds_read_b32 v122, v160 offset:68
	ds_read_b32 v123, v160 offset:72
	ds_read_b32 v124, v160 offset:76
	ds_read_b32 v125, v160 offset:96
	ds_read_b32 v136, v160 offset:100
	ds_read_b32 v137, v160 offset:104
	ds_read_b32 v130, v160 offset:108
	s_waitcnt vmcnt(0)
	v_mfma_f32_32x32x16_bf16 v[32:47], v[126:129], v[60:63], v[32:47]
	s_waitcnt lgkmcnt(14)
	s_nop 10
	v_add_f32_e32 v32, v32, v131
	v_add_f32_e32 v33, v33, v132
	s_waitcnt lgkmcnt(13)
	v_add_f32_e32 v34, v34, v118
	s_waitcnt lgkmcnt(12)
	v_add_f32_e32 v118, v35, v119
	v_max_f32_e32 v35, 0xf149f2ca, v32
	s_waitcnt lgkmcnt(11)
	v_add_f32_e32 v119, v36, v120
	v_cndmask_b32_e64 v36, v95, v33, s[96:97]
	v_cndmask_b32_e64 v35, v95, v35, s[2:3]
	s_waitcnt lgkmcnt(10)
	v_add_f32_e32 v120, v37, v121
	s_waitcnt lgkmcnt(9)
	v_add_f32_e32 v121, v38, v133
	v_cndmask_b32_e64 v37, v95, v34, s[94:95]
	v_cndmask_b32_e64 v38, v95, v118, s[92:93]
	v_max_f32_e32 v35, v35, v36
	s_waitcnt lgkmcnt(8)
	v_add_f32_e32 v126, v39, v134
	s_waitcnt lgkmcnt(7)
	v_add_f32_e32 v127, v40, v135
	v_cndmask_b32_e64 v39, v95, v119, s[90:91]
	v_cndmask_b32_e64 v40, v95, v120, s[88:89]
	v_max3_f32 v35, v35, v37, v38
	s_waitcnt lgkmcnt(6)
	v_add_f32_e32 v122, v41, v122
	s_waitcnt lgkmcnt(5)
	v_add_f32_e32 v123, v42, v123
	v_cndmask_b32_e64 v41, v95, v121, s[86:87]
	v_cndmask_b32_e64 v42, v95, v126, s[68:69]
	v_max3_f32 v35, v35, v39, v40
	s_waitcnt lgkmcnt(4)
	v_add_f32_e32 v124, v43, v124
	s_waitcnt lgkmcnt(3)
	v_add_f32_e32 v125, v44, v125
	v_cndmask_b32_e64 v43, v95, v127, s[70:71]
	v_cndmask_b32_e64 v44, v95, v122, s[72:73]
	v_max3_f32 v35, v35, v41, v42
	s_waitcnt lgkmcnt(2)
	v_add_f32_e32 v128, v45, v136
	s_waitcnt lgkmcnt(1)
	v_add_f32_e32 v129, v46, v137
	v_cndmask_b32_e64 v45, v95, v123, s[74:75]
	v_cndmask_b32_e64 v46, v95, v124, s[76:77]
	v_max3_f32 v35, v35, v43, v44
	s_waitcnt lgkmcnt(0)
	v_add_f32_e32 v130, v47, v130
	v_cndmask_b32_e64 v47, v95, v125, s[78:79]
	v_cndmask_b32_e64 v131, v95, v128, s[80:81]
	v_max3_f32 v35, v35, v45, v46
	v_cndmask_b32_e64 v132, v95, v129, s[82:83]
	v_cndmask_b32_e64 v133, v95, v130, s[84:85]
	v_max3_f32 v35, v35, v47, v131
	v_max3_f32 v35, v35, v132, v133
	v_mov_b32_e32 v36, v35
	s_nop 1
	v_permlane32_swap_b32_e32 v35, v36
	v_max3_f32 v131, v83, v35, v36
	v_sub_f32_e32 v32, v32, v131
	v_mul_f32_e32 v32, 0x3fb8aa3b, v32
	v_exp_f32_e32 v32, v32
	v_mov_b32_e32 v135, v117
	v_sub_f32_e32 v117, v118, v131
	v_sub_f32_e32 v118, v119, v131
	v_cndmask_b32_e64 v132, 0, v32, s[2:3]
	v_sub_f32_e32 v32, v33, v131
	v_mul_f32_e32 v32, 0x3fb8aa3b, v32
	v_exp_f32_e32 v32, v32
	v_sub_f32_e32 v119, v120, v131
	v_sub_f32_e32 v120, v121, v131
	v_sub_f32_e32 v121, v126, v131
	v_cndmask_b32_e64 v133, 0, v32, s[96:97]
	v_sub_f32_e32 v32, v34, v131
	v_mul_f32_e32 v32, 0x3fb8aa3b, v32
	v_exp_f32_e32 v32, v32
	v_mul_f32_e32 v117, 0x3fb8aa3b, v117
	v_mul_f32_e32 v118, 0x3fb8aa3b, v118
	v_mul_f32_e32 v119, 0x3fb8aa3b, v119
	v_cndmask_b32_e64 v134, 0, v32, s[94:95]
	v_lshlrev_b64 v[32:33], 1, v[64:65]
	v_lshl_add_u64 v[38:39], v[88:89], 0, v[32:33]
	v_lshl_add_u64 v[38:39], v[38:39], 0, v[164:165]
	v_lshl_add_u64 v[36:37], v[84:85], 0, v[32:33]
	global_load_dwordx4 v[32:35], v[38:39], off
	v_lshl_add_u64 v[46:47], v[36:37], 0, v[78:79]
	v_lshl_add_u64 v[46:47], v[46:47], 0, v[164:165]
	global_load_dwordx4 v[36:39], v[38:39], off offset:32
	s_nop 0
	s_nop 0
	global_load_dwordx4 v[40:43], v[46:47], off
	global_load_dwordx4 v[44:47], v[46:47], off offset:32
	s_nop 0
	v_sub_f32_e32 v64, v83, v131
	v_mul_f32_e32 v120, 0x3fb8aa3b, v120
	v_mul_f32_e32 v121, 0x3fb8aa3b, v121
	v_mul_f32_e32 v64, 0x3fb8aa3b, v64
	v_exp_f32_e32 v117, v117
	v_exp_f32_e32 v118, v118
	v_exp_f32_e32 v119, v119
	v_exp_f32_e32 v120, v120
	v_exp_f32_e32 v121, v121
	v_exp_f32_e32 v64, v64
	v_sub_f32_e32 v126, v127, v131
	v_sub_f32_e32 v122, v122, v131
	v_sub_f32_e32 v123, v123, v131
	v_sub_f32_e32 v124, v124, v131
	v_sub_f32_e32 v125, v125, v131
	v_sub_f32_e32 v127, v128, v131
	v_sub_f32_e32 v128, v129, v131
	v_sub_f32_e32 v129, v130, v131
	v_mov_b32_e32 v83, v131
	v_cndmask_b32_e64 v117, 0, v117, s[92:93]
	v_cndmask_b32_e64 v130, 0, v118, s[90:91]
	v_cndmask_b32_e64 v131, 0, v119, s[88:89]
	v_cndmask_b32_e64 v136, 0, v120, s[86:87]
	v_cndmask_b32_e64 v137, 0, v121, s[68:69]
	v_pk_mul_f32 v[14:15], v[14:15], v[64:65] op_sel_hi:[1,0]
	v_pk_mul_f32 v[12:13], v[12:13], v[64:65] op_sel_hi:[1,0]
	v_pk_mul_f32 v[10:11], v[10:11], v[64:65] op_sel_hi:[1,0]
	v_pk_mul_f32 v[8:9], v[8:9], v[64:65] op_sel_hi:[1,0]
	v_pk_mul_f32 v[6:7], v[6:7], v[64:65] op_sel_hi:[1,0]
	v_pk_mul_f32 v[4:5], v[4:5], v[64:65] op_sel_hi:[1,0]
	v_pk_mul_f32 v[2:3], v[2:3], v[64:65] op_sel_hi:[1,0]
	v_pk_mul_f32 v[0:1], v[0:1], v[64:65] op_sel_hi:[1,0]
	v_cvt_pk_bf16_f32 v118, v132, v133
	v_cvt_pk_bf16_f32 v119, v134, v117
	v_cvt_pk_bf16_f32 v120, v130, v131
	v_cvt_pk_bf16_f32 v121, v136, v137
	v_mul_f32_e32 v126, 0x3fb8aa3b, v126
	v_mul_f32_e32 v122, 0x3fb8aa3b, v122
	s_waitcnt vmcnt(3)
	v_permlane32_swap_b32_e32 v118, v120
	v_permlane32_swap_b32_e32 v119, v121
	s_nop 1
	v_mfma_f32_32x32x16_bf16 v[0:15], v[32:35], v[118:121], v[0:15]
	v_mul_f32_e32 v123, 0x3fb8aa3b, v123
	v_mul_f32_e32 v124, 0x3fb8aa3b, v124
	v_mul_f32_e32 v125, 0x3fb8aa3b, v125
	v_mul_f32_e32 v127, 0x3fb8aa3b, v127
	v_mul_f32_e32 v128, 0x3fb8aa3b, v128
	v_mul_f32_e32 v129, 0x3fb8aa3b, v129
	v_exp_f32_e32 v126, v126
	v_exp_f32_e32 v122, v122
	v_exp_f32_e32 v123, v123
	v_exp_f32_e32 v124, v124
	v_exp_f32_e32 v125, v125
	v_exp_f32_e32 v127, v127
	v_exp_f32_e32 v128, v128
	v_exp_f32_e32 v129, v129
	v_pk_mul_f32 v[30:31], v[30:31], v[64:65] op_sel_hi:[1,0]
	v_pk_mul_f32 v[28:29], v[28:29], v[64:65] op_sel_hi:[1,0]
	v_pk_mul_f32 v[26:27], v[26:27], v[64:65] op_sel_hi:[1,0]
	v_pk_mul_f32 v[24:25], v[24:25], v[64:65] op_sel_hi:[1,0]
	v_pk_mul_f32 v[22:23], v[22:23], v[64:65] op_sel_hi:[1,0]
	v_pk_mul_f32 v[20:21], v[20:21], v[64:65] op_sel_hi:[1,0]
	v_pk_mul_f32 v[18:19], v[18:19], v[64:65] op_sel_hi:[1,0]
	v_pk_mul_f32 v[16:17], v[16:17], v[64:65] op_sel_hi:[1,0]
	v_cndmask_b32_e64 v126, 0, v126, s[70:71]
	v_cndmask_b32_e64 v122, 0, v122, s[72:73]
	s_waitcnt vmcnt(1)
	v_mfma_f32_32x32x16_bf16 v[16:31], v[40:43], v[118:121], v[16:31]
	v_add_f32_e32 v40, 0, v132
	v_cndmask_b32_e64 v123, 0, v123, s[74:75]
	v_cndmask_b32_e64 v124, 0, v124, s[76:77]
	v_cndmask_b32_e64 v125, 0, v125, s[78:79]
	v_cndmask_b32_e64 v127, 0, v127, s[80:81]
	v_cndmask_b32_e64 v128, 0, v128, s[82:83]
	v_cndmask_b32_e64 v129, 0, v129, s[84:85]
	v_add_f32_e32 v40, v133, v40
	v_cvt_pk_bf16_f32 v32, v126, v122
	v_cvt_pk_bf16_f32 v33, v123, v124
	v_cvt_pk_bf16_f32 v34, v125, v127
	v_cvt_pk_bf16_f32 v35, v128, v129
	v_add_f32_e32 v40, v134, v40
	s_movk_i32 s89, 0x2200
	v_permlane32_swap_b32_e32 v32, v34
	v_permlane32_swap_b32_e32 v33, v35
	s_nop 1
	v_mfma_f32_32x32x16_bf16 v[0:15], v[36:39], v[32:35], v[0:15]
	v_add_f32_e32 v36, v117, v40
	v_add_f32_e32 v36, v130, v36
	v_add_f32_e32 v36, v131, v36
	v_add_f32_e32 v36, v136, v36
	v_add_f32_e32 v36, v137, v36
	v_add_f32_e32 v36, v126, v36
	v_add_f32_e32 v36, v122, v36
	s_waitcnt vmcnt(0)
	v_mfma_f32_32x32x16_bf16 v[16:31], v[44:47], v[32:35], v[16:31]
	v_add_f32_e32 v32, v123, v36
	v_add_f32_e32 v32, v124, v32
	v_add_f32_e32 v32, v125, v32
	v_add_f32_e32 v32, v127, v32
	v_add_f32_e32 v32, v128, v32
	v_add_f32_e32 v117, v129, v32
	v_fmac_f32_e32 v117, v135, v64
	s_andn2_b64 exec, exec, s[0:1]
	s_cbranch_execnz .LBB0_248
	s_or_b64 exec, exec, s[0:1]
	v_readlane_b32 s68, v254, 25
	v_readlane_b32 s72, v254, 29
	v_readlane_b32 s73, v254, 30
	v_readlane_b32 s70, v254, 27
	v_readlane_b32 s71, v254, 28
	v_readlane_b32 s82, v254, 39
	v_readlane_b32 s83, v254, 40
	v_readlane_b32 s90, v254, 45
	v_readlane_b32 s86, v254, 47
	v_readlane_b32 s72, v254, 51
	v_readlane_b32 s16, v254, 59
	v_readlane_b32 s20, v254, 53
	v_readlane_b32 s22, v254, 55
	v_readlane_b32 s2, v254, 57
	s_mov_b64 s[70:71], s[82:83]
	v_readlane_b32 s91, v254, 46
	s_mov_b32 s88, s86
	s_mov_b32 s84, s72
	v_readlane_b32 s17, v254, 60
	v_readlane_b32 s21, v254, 54
	v_readlane_b32 s23, v254, 56
	v_readlane_b32 s3, v254, 58
	v_readlane_b32 s69, v254, 26
	v_readlane_b32 s74, v254, 31
	v_readlane_b32 s75, v254, 32
	v_readlane_b32 s76, v254, 33
	v_readlane_b32 s77, v254, 34
	v_readlane_b32 s78, v254, 35
	v_readlane_b32 s79, v254, 36
	v_readlane_b32 s80, v254, 37
	v_readlane_b32 s81, v254, 38
	v_readlane_b32 s87, v254, 48
	v_readlane_b32 s73, v254, 52
	s_branch .LBB0_243

.LBB0_255:
	v_add_u32_e32 v36, v89, v69
	v_mov_b32_e32 v94, v32
	v_lshlrev_b64 v[32:33], 1, v[64:65]
	v_mad_i64_i32 v[36:37], s[0:1], v36, s55, v[82:83]
	v_add_u32_e32 v34, 16, v64
	v_mov_b32_e32 v35, v65
	v_lshl_add_u64 v[38:39], v[84:85], 0, v[32:33]
	v_lshl_add_u64 v[38:39], v[38:39], 0, v[164:165]
	v_lshl_add_u64 v[32:33], v[86:87], 0, v[32:33]
	v_lshl_add_u64 v[32:33], v[32:33], 0, v[164:165]
	v_lshl_add_u64 v[36:37], v[36:37], 0, v[76:77]
	v_lshl_add_u64 v[34:35], v[34:35], 1, v[86:87]
	v_lshl_add_u64 v[34:35], v[34:35], 0, v[164:165]
	global_load_dwordx4 v[96:99], v[38:39], off
	global_load_dwordx4 v[100:103], v[38:39], off offset:32
	global_load_dwordx4 v[104:107], v[32:33], off
	global_load_dwordx4 v[108:111], v[34:35], off
	v_add_co_u32_e64 v32, s[0:1], s33, v36
	v_lshl_add_u64 v[120:121], v[36:37], 0, s[42:43]
	s_nop 0
	v_addc_co_u32_e64 v33, s[0:1], 0, v37, s[0:1]
	global_load_dwordx4 v[32:35], v[32:33], off
	s_nop 0
	global_load_dwordx4 v[112:115], v[120:121], off offset:32
	global_load_dwordx4 v[116:119], v[120:121], off offset:96
	v_add_u32_e32 v40, v89, v75
	v_add_u32_e32 v154, s56, v40
	v_add_u32_e32 v154, -1, v154
	v_lshl_add_u32 v156, s56, 1, -1
	global_load_dwordx4 v[120:123], v[120:121], off offset:64
	s_waitcnt vmcnt(19)
	s_waitcnt vmcnt(18)
	v_subrev_u32_e32 v149, 0, v154
	v_subrev_u32_e32 v150, 1, v154
	v_subrev_u32_e32 v151, 2, v154
	v_add_u32_e32 v71, 1, v71
	v_cmp_ge_u32_e32 vcc, v71, v73
	v_subrev_u32_e32 v95, 3, v154
	s_or_b64 s[50:51], vcc, s[50:51]
	v_cmp_gt_u32_e32 vcc, v156, v150
	v_cmp_gt_u32_e64 s[2:3], v156, v95
	v_cmp_gt_u32_e64 s[28:29], v156, v149
	v_cmp_gt_u32_e64 s[0:1], v156, v151
	v_subrev_u32_e32 v124, 16, v154
	v_cmp_gt_u32_e64 s[12:13], v156, v124
	v_subrev_u32_e32 v75, 32, v75
	v_add_u32_e32 v64, 32, v64
	v_add_u32_e32 v69, 32, v69
	s_waitcnt vmcnt(3)
	v_mfma_f32_32x32x16_bf16 v[32:47], v[32:35], v[48:51], 0
	s_waitcnt vmcnt(2)
	v_mfma_f32_32x32x16_bf16 v[32:47], v[112:115], v[52:55], v[32:47]
	v_subrev_u32_e32 v112, 8, v154
	v_cmp_gt_u32_e64 s[4:5], v156, v112
	v_subrev_u32_e32 v113, 9, v154
	v_subrev_u32_e32 v114, 10, v154
	v_subrev_u32_e32 v115, 11, v154
	v_cmp_gt_u32_e64 s[6:7], v156, v113
	v_cmp_gt_u32_e64 s[8:9], v156, v114
	s_waitcnt vmcnt(0)
	v_mfma_f32_32x32x16_bf16 v[32:47], v[120:123], v[56:59], v[32:47]
	v_subrev_u32_e32 v125, 17, v154
	v_cmp_gt_u32_e64 s[10:11], v156, v115
	v_subrev_u32_e32 v120, 18, v154
	v_subrev_u32_e32 v121, 19, v154
	v_cmp_gt_u32_e64 s[14:15], v156, v125
	v_subrev_u32_e32 v122, 24, v154
	v_subrev_u32_e32 v123, 25, v154
	v_mfma_f32_32x32x16_bf16 v[32:47], v[116:119], v[60:63], v[32:47]
	v_cmp_gt_u32_e64 s[16:17], v156, v120
	v_cmp_gt_u32_e64 s[18:19], v156, v121
	v_subrev_u32_e32 v126, 26, v154
	v_subrev_u32_e32 v127, 27, v154
	v_cmp_gt_u32_e64 s[20:21], v156, v122
	v_cmp_gt_u32_e64 s[22:23], v156, v123
	v_cmp_gt_u32_e64 s[24:25], v156, v126
	s_nop 4
	v_max_f32_e32 v95, v32, v32
	v_cndmask_b32_e32 v112, v93, v33, vcc
	v_max_f32_e32 v95, 0xf149f2ca, v95
	v_max_f32_e32 v112, v112, v112
	v_cndmask_b32_e64 v95, v93, v95, s[28:29]
	v_cndmask_b32_e64 v113, v93, v34, s[0:1]
	v_cndmask_b32_e64 v114, v93, v35, s[2:3]
	v_max_f32_e32 v95, v95, v112
	v_cndmask_b32_e64 v115, v93, v36, s[4:5]
	v_cndmask_b32_e64 v116, v93, v37, s[6:7]
	v_max3_f32 v95, v95, v113, v114
	v_cndmask_b32_e64 v117, v93, v38, s[8:9]
	v_cndmask_b32_e64 v118, v93, v39, s[10:11]
	v_max3_f32 v95, v95, v115, v116
	v_cndmask_b32_e64 v119, v93, v40, s[12:13]
	v_cndmask_b32_e64 v120, v93, v41, s[14:15]
	v_max3_f32 v95, v95, v117, v118
	v_cndmask_b32_e64 v121, v93, v42, s[16:17]
	v_cndmask_b32_e64 v122, v93, v43, s[18:19]
	v_max3_f32 v95, v95, v119, v120
	v_cmp_gt_u32_e64 s[26:27], v156, v127
	v_cndmask_b32_e64 v123, v93, v44, s[20:21]
	v_cndmask_b32_e64 v124, v93, v45, s[22:23]
	v_max3_f32 v95, v95, v121, v122
	v_cndmask_b32_e64 v125, v93, v46, s[24:25]
	v_cndmask_b32_e64 v126, v93, v47, s[26:27]
	v_max3_f32 v95, v95, v123, v124
	v_max3_f32 v95, v95, v125, v126
	v_mov_b32_e32 v112, v95
	s_nop 1
	v_permlane32_swap_b32_e32 v95, v112
	v_max3_f32 v95, v81, v95, v112
	v_sub_f32_e32 v32, v32, v95
	v_sub_f32_e32 v33, v33, v95
	v_sub_f32_e32 v34, v34, v95
	v_sub_f32_e32 v35, v35, v95
	v_sub_f32_e32 v36, v36, v95
	v_sub_f32_e32 v37, v37, v95
	v_sub_f32_e32 v38, v38, v95
	v_sub_f32_e32 v39, v39, v95
	v_sub_f32_e32 v112, v81, v95
	v_mul_f32_e32 v32, 0x3fb8aa3b, v32
	v_mul_f32_e32 v33, 0x3fb8aa3b, v33
	v_mul_f32_e32 v34, 0x3fb8aa3b, v34
	v_mul_f32_e32 v35, 0x3fb8aa3b, v35
	v_mul_f32_e32 v36, 0x3fb8aa3b, v36
	v_mul_f32_e32 v37, 0x3fb8aa3b, v37
	v_mul_f32_e32 v38, 0x3fb8aa3b, v38
	v_mul_f32_e32 v39, 0x3fb8aa3b, v39
	v_sub_f32_e32 v40, v40, v95
	v_sub_f32_e32 v41, v41, v95
	v_sub_f32_e32 v42, v42, v95
	v_sub_f32_e32 v43, v43, v95
	v_sub_f32_e32 v44, v44, v95
	v_sub_f32_e32 v45, v45, v95
	v_sub_f32_e32 v46, v46, v95
	v_sub_f32_e32 v47, v47, v95
	v_mov_b32_e32 v81, v95
	v_mul_f32_e32 v95, 0x3fb8aa3b, v112
	v_exp_f32_e32 v32, v32
	v_exp_f32_e32 v33, v33
	v_exp_f32_e32 v34, v34
	v_exp_f32_e32 v35, v35
	v_exp_f32_e32 v112, v36
	v_exp_f32_e32 v37, v37
	v_exp_f32_e32 v38, v38
	v_exp_f32_e32 v39, v39
	v_exp_f32_e32 v36, v95
	v_cndmask_b32_e64 v95, 0, v32, s[28:29]
	v_cndmask_b32_e32 v113, 0, v33, vcc
	v_cndmask_b32_e64 v114, 0, v34, s[0:1]
	v_cndmask_b32_e64 v115, 0, v35, s[2:3]
	v_cndmask_b32_e64 v112, 0, v112, s[4:5]
	v_cndmask_b32_e64 v37, 0, v37, s[6:7]
	v_cndmask_b32_e64 v38, 0, v38, s[8:9]
	v_cndmask_b32_e64 v39, 0, v39, s[10:11]
	v_pk_mul_f32 v[14:15], v[14:15], v[36:37] op_sel_hi:[1,0]
	v_pk_mul_f32 v[12:13], v[12:13], v[36:37] op_sel_hi:[1,0]
	v_pk_mul_f32 v[10:11], v[10:11], v[36:37] op_sel_hi:[1,0]
	v_pk_mul_f32 v[8:9], v[8:9], v[36:37] op_sel_hi:[1,0]
	v_pk_mul_f32 v[6:7], v[6:7], v[36:37] op_sel_hi:[1,0]
	v_pk_mul_f32 v[4:5], v[4:5], v[36:37] op_sel_hi:[1,0]
	v_pk_mul_f32 v[2:3], v[2:3], v[36:37] op_sel_hi:[1,0]
	v_pk_mul_f32 v[0:1], v[0:1], v[36:37] op_sel_hi:[1,0]
	v_pk_mul_f32 v[30:31], v[30:31], v[36:37] op_sel_hi:[1,0]
	v_cvt_pk_bf16_f32 v32, v95, v113
	v_cvt_pk_bf16_f32 v33, v114, v115
	v_cvt_pk_bf16_f32 v34, v112, v37
	v_cvt_pk_bf16_f32 v35, v38, v39
	v_pk_mul_f32 v[28:29], v[28:29], v[36:37] op_sel_hi:[1,0]
	v_pk_mul_f32 v[26:27], v[26:27], v[36:37] op_sel_hi:[1,0]
	v_pk_mul_f32 v[24:25], v[24:25], v[36:37] op_sel_hi:[1,0]
	v_pk_mul_f32 v[22:23], v[22:23], v[36:37] op_sel_hi:[1,0]
	v_pk_mul_f32 v[20:21], v[20:21], v[36:37] op_sel_hi:[1,0]
	v_pk_mul_f32 v[18:19], v[18:19], v[36:37] op_sel_hi:[1,0]
	v_pk_mul_f32 v[16:17], v[16:17], v[36:37] op_sel_hi:[1,0]
	v_add_f32_e32 v95, 0, v95
	v_permlane32_swap_b32_e32 v32, v34
	v_permlane32_swap_b32_e32 v33, v35
	s_nop 1
	v_mfma_f32_32x32x16_bf16 v[0:15], v[96:99], v[32:35], v[0:15]
	v_add_f32_e32 v95, v113, v95
	v_mul_f32_e32 v40, 0x3fb8aa3b, v40
	v_mul_f32_e32 v41, 0x3fb8aa3b, v41
	v_mul_f32_e32 v42, 0x3fb8aa3b, v42
	v_mul_f32_e32 v43, 0x3fb8aa3b, v43
	v_mul_f32_e32 v44, 0x3fb8aa3b, v44
	v_mul_f32_e32 v45, 0x3fb8aa3b, v45
	v_mfma_f32_32x32x16_bf16 v[16:31], v[104:107], v[32:35], v[16:31]
	v_mul_f32_e32 v46, 0x3fb8aa3b, v46
	v_mul_f32_e32 v47, 0x3fb8aa3b, v47
	v_add_f32_e32 v95, v114, v95
	v_exp_f32_e32 v40, v40
	v_exp_f32_e32 v41, v41
	v_exp_f32_e32 v42, v42
	v_exp_f32_e32 v43, v43
	v_exp_f32_e32 v44, v44
	v_exp_f32_e32 v45, v45
	v_exp_f32_e32 v46, v46
	v_exp_f32_e32 v47, v47
	v_add_f32_e32 v95, v115, v95
	v_add_f32_e32 v95, v112, v95
	v_add_f32_e32 v37, v37, v95
	v_add_f32_e32 v37, v38, v37
	v_cndmask_b32_e64 v40, 0, v40, s[12:13]
	v_cndmask_b32_e64 v41, 0, v41, s[14:15]
	v_cndmask_b32_e64 v42, 0, v42, s[16:17]
	v_cndmask_b32_e64 v43, 0, v43, s[18:19]
	v_cndmask_b32_e64 v44, 0, v44, s[20:21]
	v_cndmask_b32_e64 v45, 0, v45, s[22:23]
	v_cndmask_b32_e64 v46, 0, v46, s[24:25]
	v_cndmask_b32_e64 v47, 0, v47, s[26:27]
	v_add_f32_e32 v37, v39, v37
	v_cvt_pk_bf16_f32 v32, v40, v41
	v_cvt_pk_bf16_f32 v33, v42, v43
	v_cvt_pk_bf16_f32 v34, v44, v45
	v_cvt_pk_bf16_f32 v35, v46, v47
	v_add_f32_e32 v37, v40, v37
	v_add_f32_e32 v37, v41, v37
	v_permlane32_swap_b32_e32 v32, v34
	v_permlane32_swap_b32_e32 v33, v35
	s_nop 1
	v_mfma_f32_32x32x16_bf16 v[0:15], v[100:103], v[32:35], v[0:15]
	v_mfma_f32_32x32x16_bf16 v[16:31], v[108:111], v[32:35], v[16:31]
	v_add_f32_e32 v32, v42, v37
	v_add_f32_e32 v32, v43, v32
	v_add_f32_e32 v32, v44, v32
	v_add_f32_e32 v32, v45, v32
	v_add_f32_e32 v32, v46, v32
	v_add_f32_e32 v32, v47, v32
	v_fmac_f32_e32 v32, v94, v36
	s_andn2_b64 exec, exec, s[50:51]
	s_cbranch_execnz .LBB0_255
	s_or_b64 exec, exec, s[50:51]
	s_branch .LBB0_252

.LBB0_833:
	v_add_u32_e32 v32, s33, v91
	v_lshl_or_b32 v64, v32, 6, v89
	v_sub_u32_e32 v33, v32, v87
	v_cmp_ge_u32_e32 vcc, v32, v111
	v_cmp_lt_u32_e64 s[2:3], v32, v113
	v_add_u32_e32 v32, v112, v64
	v_max_i32_e32 v33, -7, v33
	s_and_b64 s[86:87], vcc, s[2:3]
	v_mad_i64_i32 v[36:37], s[2:3], v32, s85, v[100:101]
	v_add_u32_e32 v38, 7, v33
	global_load_dwordx4 v[32:35], v[36:37], off offset:1024
	global_load_dwordx4 v[132:135], v[36:37], off offset:1056
	global_load_dwordx4 v[136:139], v[36:37], off offset:1088
	global_load_dwordx4 v[140:143], v[36:37], off offset:1120
	v_min_u32_e32 v36, 14, v38
	s_movk_i32 vcc_lo, 0x7c
	v_mad_u32_u24 v131, v36, vcc_lo, v105
	v_lshl_add_u32 v160, v161, 2, v131
	ds_read_b32 v144, v160
	ds_read_b32 v145, v160 offset:4
	v_readlane_b32 s2, v254, 61
	v_readlane_b32 s3, v254, 62
	s_and_b64 s[2:3], s[86:87], s[2:3]
	s_and_b64 s[4:5], s[86:87], s[8:9]
	s_and_b64 s[96:97], s[86:87], s[12:13]
	s_and_b64 s[94:95], s[86:87], s[16:17]
	s_and_b64 s[4:5], s[4:5], s[10:11]
	s_and_b64 s[2:3], s[2:3], s[6:7]
	s_and_b64 s[92:93], s[86:87], s[20:21]
	s_and_b64 s[90:91], s[86:87], s[24:25]
	s_and_b64 s[96:97], s[96:97], s[14:15]
	s_and_b64 s[94:95], s[94:95], s[18:19]
	s_and_b64 s[88:89], s[86:87], s[28:29]
	s_and_b64 s[70:71], s[86:87], s[34:35]
	s_and_b64 s[92:93], s[92:93], s[22:23]
	s_and_b64 s[90:91], s[90:91], s[26:27]
	s_and_b64 s[72:73], s[86:87], s[38:39]
	s_and_b64 s[74:75], s[86:87], s[42:43]
	s_and_b64 s[88:89], s[88:89], s[30:31]
	s_and_b64 s[70:71], s[70:71], s[36:37]
	s_and_b64 s[76:77], s[86:87], s[46:47]
	s_and_b64 s[78:79], s[86:87], s[50:51]
	s_and_b64 s[72:73], s[72:73], s[40:41]
	s_and_b64 s[74:75], s[74:75], s[44:45]
	s_and_b64 s[80:81], s[86:87], s[54:55]
	s_and_b64 s[82:83], s[86:87], s[58:59]
	s_and_b64 s[76:77], s[76:77], s[48:49]
	s_and_b64 s[78:79], s[78:79], s[52:53]
	s_and_b64 s[84:85], s[86:87], s[62:63]
	s_and_b64 s[86:87], s[86:87], s[66:67]
	s_and_b64 s[80:81], s[80:81], s[56:57]
	s_and_b64 s[82:83], s[82:83], s[60:61]
	s_and_b64 s[84:85], s[84:85], s[64:65]
	s_and_b64 s[86:87], s[86:87], s[68:69]
	s_add_i32 s33, s33, 1
	v_cmp_ge_i32_e32 vcc, s33, v110
	s_or_b64 s[0:1], vcc, s[0:1]
	s_waitcnt vmcnt(3)
	v_mfma_f32_32x32x16_bf16 v[32:47], v[32:35], v[48:51], 0
	s_waitcnt vmcnt(2)
	v_mfma_f32_32x32x16_bf16 v[32:47], v[132:135], v[52:55], v[32:47]
	ds_read_b32 v132, v160 offset:8
	ds_read_b32 v133, v160 offset:12
	ds_read_b32 v134, v160 offset:32
	ds_read_b32 v135, v160 offset:36
	ds_read_b32 v146, v160 offset:40
	ds_read_b32 v147, v160 offset:44
	ds_read_b32 v148, v160 offset:64
	s_waitcnt vmcnt(1)
	v_mfma_f32_32x32x16_bf16 v[32:47], v[136:139], v[56:59], v[32:47]
	ds_read_b32 v136, v160 offset:68
	ds_read_b32 v137, v160 offset:72
	ds_read_b32 v138, v160 offset:76
	ds_read_b32 v139, v160 offset:96
	ds_read_b32 v149, v160 offset:100
	ds_read_b32 v150, v160 offset:104
	ds_read_b32 v131, v160 offset:108
	s_waitcnt vmcnt(0)
	v_mfma_f32_32x32x16_bf16 v[32:47], v[140:143], v[60:63], v[32:47]
	s_waitcnt lgkmcnt(14)
	s_nop 10
	v_add_f32_e32 v32, v32, v144
	v_add_f32_e32 v33, v33, v145
	s_waitcnt lgkmcnt(13)
	v_add_f32_e32 v34, v34, v132
	s_waitcnt lgkmcnt(12)
	v_add_f32_e32 v132, v35, v133
	v_max_f32_e32 v35, 0xf149f2ca, v32
	s_waitcnt lgkmcnt(11)
	v_add_f32_e32 v133, v36, v134
	v_cndmask_b32_e64 v36, v109, v33, s[4:5]
	v_cndmask_b32_e64 v35, v109, v35, s[2:3]
	s_waitcnt lgkmcnt(10)
	v_add_f32_e32 v134, v37, v135
	s_waitcnt lgkmcnt(9)
	v_add_f32_e32 v135, v38, v146
	v_cndmask_b32_e64 v37, v109, v34, s[96:97]
	v_cndmask_b32_e64 v38, v109, v132, s[94:95]
	v_max_f32_e32 v35, v35, v36
	s_waitcnt lgkmcnt(8)
	v_add_f32_e32 v140, v39, v147
	s_waitcnt lgkmcnt(7)
	v_add_f32_e32 v141, v40, v148
	v_cndmask_b32_e64 v39, v109, v133, s[92:93]
	v_cndmask_b32_e64 v40, v109, v134, s[90:91]
	v_max3_f32 v35, v35, v37, v38
	s_waitcnt lgkmcnt(6)
	v_add_f32_e32 v136, v41, v136
	s_waitcnt lgkmcnt(5)
	v_add_f32_e32 v137, v42, v137
	v_cndmask_b32_e64 v41, v109, v135, s[88:89]
	v_cndmask_b32_e64 v42, v109, v140, s[70:71]
	v_max3_f32 v35, v35, v39, v40
	s_waitcnt lgkmcnt(4)
	v_add_f32_e32 v138, v43, v138
	s_waitcnt lgkmcnt(3)
	v_add_f32_e32 v139, v44, v139
	v_cndmask_b32_e64 v43, v109, v141, s[72:73]
	v_cndmask_b32_e64 v44, v109, v136, s[74:75]
	v_max3_f32 v35, v35, v41, v42
	s_waitcnt lgkmcnt(2)
	v_add_f32_e32 v142, v45, v149
	s_waitcnt lgkmcnt(1)
	v_add_f32_e32 v143, v46, v150
	v_cndmask_b32_e64 v45, v109, v137, s[76:77]
	v_cndmask_b32_e64 v46, v109, v138, s[78:79]
	v_max3_f32 v35, v35, v43, v44
	s_waitcnt lgkmcnt(0)
	v_add_f32_e32 v131, v47, v131
	v_cndmask_b32_e64 v47, v109, v139, s[80:81]
	v_cndmask_b32_e64 v144, v109, v142, s[82:83]
	v_max3_f32 v35, v35, v45, v46
	v_cndmask_b32_e64 v145, v109, v143, s[84:85]
	v_cndmask_b32_e64 v146, v109, v131, s[86:87]
	v_max3_f32 v35, v35, v47, v144
	v_max3_f32 v35, v35, v145, v146
	v_mov_b32_e32 v36, v35
	s_nop 1
	v_permlane32_swap_b32_e32 v35, v36
	v_max3_f32 v144, v97, v35, v36
	v_sub_f32_e32 v32, v32, v144
	v_mul_f32_e32 v32, 0x3fb8aa3b, v32
	v_exp_f32_e32 v32, v32
	v_mov_b32_e32 v148, v130
	v_sub_f32_e32 v130, v132, v144
	v_sub_f32_e32 v132, v133, v144
	v_cndmask_b32_e64 v145, 0, v32, s[2:3]
	v_sub_f32_e32 v32, v33, v144
	v_mul_f32_e32 v32, 0x3fb8aa3b, v32
	v_exp_f32_e32 v32, v32
	v_sub_f32_e32 v133, v134, v144
	v_sub_f32_e32 v134, v135, v144
	v_sub_f32_e32 v135, v140, v144
	v_cndmask_b32_e64 v146, 0, v32, s[4:5]
	v_sub_f32_e32 v32, v34, v144
	v_mul_f32_e32 v32, 0x3fb8aa3b, v32
	v_exp_f32_e32 v32, v32
	v_sub_f32_e32 v131, v131, v144
	v_mul_f32_e32 v130, 0x3fb8aa3b, v130
	v_mul_f32_e32 v132, 0x3fb8aa3b, v132
	v_cndmask_b32_e64 v147, 0, v32, s[96:97]
	v_lshlrev_b64 v[32:33], 1, v[64:65]
	v_lshl_add_u64 v[38:39], v[102:103], 0, v[32:33]
	v_lshl_add_u64 v[38:39], v[38:39], 0, v[164:165]
	v_lshl_add_u64 v[36:37], v[98:99], 0, v[32:33]
	global_load_dwordx4 v[32:35], v[38:39], off
	v_lshl_add_u64 v[46:47], v[36:37], 0, v[92:93]
	v_lshl_add_u64 v[46:47], v[46:47], 0, v[164:165]
	global_load_dwordx4 v[36:39], v[38:39], off offset:32
	s_nop 0
	s_nop 0
	global_load_dwordx4 v[40:43], v[46:47], off
	global_load_dwordx4 v[44:47], v[46:47], off offset:32
	s_nop 0
	v_sub_f32_e32 v64, v97, v144
	v_mul_f32_e32 v133, 0x3fb8aa3b, v133
	v_mul_f32_e32 v134, 0x3fb8aa3b, v134
	v_mul_f32_e32 v135, 0x3fb8aa3b, v135
	v_mul_f32_e32 v64, 0x3fb8aa3b, v64
	v_mul_f32_e32 v131, 0x3fb8aa3b, v131
	v_exp_f32_e32 v130, v130
	v_exp_f32_e32 v132, v132
	v_exp_f32_e32 v133, v133
	v_exp_f32_e32 v134, v134
	v_exp_f32_e32 v135, v135
	v_exp_f32_e32 v131, v131
	v_exp_f32_e32 v64, v64
	v_sub_f32_e32 v140, v141, v144
	v_sub_f32_e32 v136, v136, v144
	v_sub_f32_e32 v137, v137, v144
	v_sub_f32_e32 v138, v138, v144
	v_sub_f32_e32 v139, v139, v144
	v_sub_f32_e32 v141, v142, v144
	v_sub_f32_e32 v142, v143, v144
	v_mov_b32_e32 v97, v144
	v_cndmask_b32_e64 v143, 0, v130, s[94:95]
	v_cndmask_b32_e64 v144, 0, v132, s[92:93]
	v_cndmask_b32_e64 v149, 0, v133, s[90:91]
	v_cndmask_b32_e64 v134, 0, v134, s[88:89]
	v_cndmask_b32_e64 v135, 0, v135, s[70:71]
	v_cndmask_b32_e64 v150, 0, v131, s[86:87]
	v_pk_mul_f32 v[14:15], v[14:15], v[64:65] op_sel_hi:[1,0]
	v_pk_mul_f32 v[12:13], v[12:13], v[64:65] op_sel_hi:[1,0]
	v_pk_mul_f32 v[10:11], v[10:11], v[64:65] op_sel_hi:[1,0]
	v_pk_mul_f32 v[8:9], v[8:9], v[64:65] op_sel_hi:[1,0]
	v_pk_mul_f32 v[6:7], v[6:7], v[64:65] op_sel_hi:[1,0]
	v_pk_mul_f32 v[4:5], v[4:5], v[64:65] op_sel_hi:[1,0]
	v_pk_mul_f32 v[2:3], v[2:3], v[64:65] op_sel_hi:[1,0]
	v_pk_mul_f32 v[0:1], v[0:1], v[64:65] op_sel_hi:[1,0]
	v_cvt_pk_bf16_f32 v130, v145, v146
	v_cvt_pk_bf16_f32 v131, v147, v143
	v_cvt_pk_bf16_f32 v132, v144, v149
	v_cvt_pk_bf16_f32 v133, v134, v135
	v_mul_f32_e32 v140, 0x3fb8aa3b, v140
	v_mul_f32_e32 v136, 0x3fb8aa3b, v136
	s_waitcnt vmcnt(3)
	v_permlane32_swap_b32_e32 v130, v132
	v_permlane32_swap_b32_e32 v131, v133
	s_nop 1
	v_mfma_f32_32x32x16_bf16 v[0:15], v[32:35], v[130:133], v[0:15]
	v_mul_f32_e32 v137, 0x3fb8aa3b, v137
	v_mul_f32_e32 v138, 0x3fb8aa3b, v138
	v_mul_f32_e32 v139, 0x3fb8aa3b, v139
	v_mul_f32_e32 v141, 0x3fb8aa3b, v141
	v_mul_f32_e32 v142, 0x3fb8aa3b, v142
	v_exp_f32_e32 v140, v140
	v_exp_f32_e32 v136, v136
	v_exp_f32_e32 v137, v137
	v_exp_f32_e32 v138, v138
	v_exp_f32_e32 v139, v139
	v_exp_f32_e32 v141, v141
	v_exp_f32_e32 v142, v142
	v_pk_mul_f32 v[30:31], v[30:31], v[64:65] op_sel_hi:[1,0]
	v_pk_mul_f32 v[28:29], v[28:29], v[64:65] op_sel_hi:[1,0]
	v_pk_mul_f32 v[26:27], v[26:27], v[64:65] op_sel_hi:[1,0]
	v_pk_mul_f32 v[24:25], v[24:25], v[64:65] op_sel_hi:[1,0]
	v_pk_mul_f32 v[22:23], v[22:23], v[64:65] op_sel_hi:[1,0]
	v_pk_mul_f32 v[20:21], v[20:21], v[64:65] op_sel_hi:[1,0]
	v_pk_mul_f32 v[18:19], v[18:19], v[64:65] op_sel_hi:[1,0]
	v_pk_mul_f32 v[16:17], v[16:17], v[64:65] op_sel_hi:[1,0]
	v_cndmask_b32_e64 v140, 0, v140, s[72:73]
	v_cndmask_b32_e64 v136, 0, v136, s[74:75]
	s_waitcnt vmcnt(1)
	v_mfma_f32_32x32x16_bf16 v[16:31], v[40:43], v[130:133], v[16:31]
	v_add_f32_e32 v40, 0, v145
	v_cndmask_b32_e64 v137, 0, v137, s[76:77]
	v_cndmask_b32_e64 v138, 0, v138, s[78:79]
	v_cndmask_b32_e64 v139, 0, v139, s[80:81]
	v_cndmask_b32_e64 v141, 0, v141, s[82:83]
	v_cndmask_b32_e64 v142, 0, v142, s[84:85]
	v_add_f32_e32 v40, v146, v40
	v_cvt_pk_bf16_f32 v32, v140, v136
	v_cvt_pk_bf16_f32 v33, v137, v138
	v_cvt_pk_bf16_f32 v34, v139, v141
	v_cvt_pk_bf16_f32 v35, v142, v150
	v_add_f32_e32 v40, v147, v40
	s_movk_i32 s85, 0x2200
	v_permlane32_swap_b32_e32 v32, v34
	v_permlane32_swap_b32_e32 v33, v35
	s_nop 1
	v_mfma_f32_32x32x16_bf16 v[0:15], v[36:39], v[32:35], v[0:15]
	v_add_f32_e32 v36, v143, v40
	v_add_f32_e32 v36, v144, v36
	v_add_f32_e32 v36, v149, v36
	v_add_f32_e32 v36, v134, v36
	v_add_f32_e32 v36, v135, v36
	v_add_f32_e32 v36, v140, v36
	v_add_f32_e32 v36, v136, v36
	s_waitcnt vmcnt(0)
	v_mfma_f32_32x32x16_bf16 v[16:31], v[44:47], v[32:35], v[16:31]
	v_add_f32_e32 v32, v137, v36
	v_add_f32_e32 v32, v138, v32
	v_add_f32_e32 v32, v139, v32
	v_add_f32_e32 v32, v141, v32
	v_add_f32_e32 v32, v142, v32
	v_add_f32_e32 v130, v150, v32
	v_fmac_f32_e32 v130, v148, v64
	s_andn2_b64 exec, exec, s[0:1]
	s_cbranch_execnz .LBB0_833
	s_or_b64 exec, exec, s[0:1]
	v_readlane_b32 s68, v254, 25
	v_readlane_b32 s72, v254, 29
	v_readlane_b32 s73, v254, 30
	v_readlane_b32 s88, v254, 47
	v_readlane_b32 s70, v254, 27
	v_readlane_b32 s71, v254, 28
	v_readlane_b32 s82, v254, 39
	v_readlane_b32 s83, v254, 40
	v_readlane_b32 s90, v254, 45
	v_readlane_b32 s89, v254, 48
	v_readlane_b32 s72, v254, 51
	v_readlane_b32 s92, v254, 53
	v_readlane_b32 s16, v254, 59
	v_readlane_b32 s18, v254, 41
	v_readlane_b32 s20, v254, 43
	v_readlane_b32 s2, v254, 57
	s_mov_b64 s[70:71], s[82:83]
	v_readlane_b32 s91, v254, 46
	s_mov_b32 s84, s72
	v_readlane_b32 s89, v254, 49
	v_readlane_b32 s93, v254, 54
	v_readlane_b32 s17, v254, 60
	v_readlane_b32 s19, v254, 42
	v_readlane_b32 s21, v254, 44
	v_readlane_b32 s3, v254, 58
	v_readlane_b32 s69, v254, 26
	v_readlane_b32 s74, v254, 31
	v_readlane_b32 s75, v254, 32
	v_readlane_b32 s76, v254, 33
	v_readlane_b32 s77, v254, 34
	v_readlane_b32 s78, v254, 35
	v_readlane_b32 s79, v254, 36
	v_readlane_b32 s80, v254, 37
	v_readlane_b32 s81, v254, 38
	v_readlane_b32 s73, v254, 52
	s_branch .LBB0_828
